# v114 + P0 mod item touches all 128 weight rows of its K range before the K-loop (one exposed HBM round trip instead of eight)
# baseline (speedup 1.0000x reference)
; __device__ __forceinline__ void p0_mod_item(const Args& a, LAS unsigned char* lds, int it, int tid, int lane, int wave) {
;     const int l = it / 96, col0 = (it % 96) * 32;
;     const float* W = a.in[7] + (size_t)l * D * 3072;
;     const int n = lane & 31, kq = lane >> 5;
;     f32x16 acc[5];
; #pragma unroll
;     for (int rt = 0; rt < 5; ++rt)
; #pragma unroll
;         for (int i = 0; i < 16; ++i) acc[rt][i] = 0.f;
;     const u32x4* tabs = (const u32x4*)(a.ws + WS_SILU) + (size_t)(wave * 8) * 64 + lane;
;     const float* wp = W + (size_t)(wave * 128 + 8 * kq) * 3072 + col0 + n;
; #pragma unroll 1
;     for (int kp = 0; kp < 4; ++kp) {
;         float wv[2][8]; u32x4 af[2][5];
; #pragma unroll
;         for (int h = 0; h < 2; ++h) {
; #pragma unroll
;             for (int j = 0; j < 8; ++j) wv[h][j] = __builtin_nontemporal_load(wp + (size_t)(h * 16 + j) * 3072);
.LBB0_74:
	s_mul_hi_i32 s4, s44, 0x2aaaaaab
	s_lshr_b32 s5, s4, 31
	s_ashr_i32 s4, s4, 4
	s_add_i32 s45, s4, s5
	s_mul_i32 s4, s45, 0x60
	s_sub_i32 s4, s44, s4
	s_lshl_b32 s18, s4, 5
	v_mad_i64_i32 v[0:1], s[4:5], s45, v95, v[86:87]
	s_ashr_i32 s19, s18, 31
	v_lshl_add_u64 v[0:1], s[18:19], 2, v[0:1]
	v_lshl_add_u64 v[90:91], v[0:1], 0, v[82:83]
	s_mov_b64 s[4:5], 0
	v_mov_b32_e32 v0, 0
	v_mov_b32_e32 v1, v83
	v_mov_b32_e32 v2, v83
	v_mov_b32_e32 v3, v83
	v_mov_b32_e32 v4, v83
	v_mov_b32_e32 v5, v83
	v_mov_b32_e32 v6, v83
	v_mov_b32_e32 v7, v83
	v_mov_b32_e32 v8, v83
	v_mov_b32_e32 v9, v83
	v_mov_b32_e32 v10, v83
	v_mov_b32_e32 v11, v83
	v_mov_b32_e32 v12, v83
	v_mov_b32_e32 v13, v83
	v_mov_b32_e32 v14, v83
	v_mov_b32_e32 v15, v83
	v_mov_b32_e32 v16, 0
	v_mov_b32_e32 v17, v83
	v_mov_b32_e32 v18, v83
	v_mov_b32_e32 v19, v83
	v_mov_b32_e32 v20, v83
	v_mov_b32_e32 v21, v83
	v_mov_b32_e32 v22, v83
	v_mov_b32_e32 v23, v83
	v_mov_b32_e32 v24, v83
	v_mov_b32_e32 v25, v83
	v_mov_b32_e32 v26, v83
	v_mov_b32_e32 v27, v83
	v_mov_b32_e32 v28, v83
	v_mov_b32_e32 v29, v83
	v_mov_b32_e32 v30, v83
	v_mov_b32_e32 v31, v83
	v_mov_b32_e32 v32, 0
	v_mov_b32_e32 v33, v83
	v_mov_b32_e32 v34, v83
	v_mov_b32_e32 v35, v83
	v_mov_b32_e32 v36, v83
	v_mov_b32_e32 v37, v83
	v_mov_b32_e32 v38, v83
	v_mov_b32_e32 v39, v83
	v_mov_b32_e32 v40, v83
	v_mov_b32_e32 v41, v83
	v_mov_b32_e32 v42, v83
	v_mov_b32_e32 v43, v83
	v_mov_b32_e32 v44, v83
	v_mov_b32_e32 v45, v83
	v_mov_b32_e32 v46, v83
	v_mov_b32_e32 v47, v83
	v_mov_b32_e32 v48, 0
	v_mov_b32_e32 v49, v83
	v_mov_b32_e32 v50, v83
	v_mov_b32_e32 v51, v83
	v_mov_b32_e32 v52, v83
	v_mov_b32_e32 v53, v83
	v_mov_b32_e32 v54, v83
	v_mov_b32_e32 v55, v83
	v_mov_b32_e32 v56, v83
	v_mov_b32_e32 v57, v83
	v_mov_b32_e32 v58, v83
	v_mov_b32_e32 v59, v83
	v_mov_b32_e32 v60, v83
	v_mov_b32_e32 v61, v83
	v_mov_b32_e32 v62, v83
	v_mov_b32_e32 v63, v83
	v_mov_b32_e32 v64, 0
	v_mov_b32_e32 v65, v83
	v_mov_b32_e32 v66, v83
	v_mov_b32_e32 v67, v83
	v_mov_b32_e32 v68, v83
	v_mov_b32_e32 v69, v83
	v_mov_b32_e32 v70, v83
	v_mov_b32_e32 v71, v83
	v_mov_b32_e32 v72, v83
	v_mov_b32_e32 v73, v83
	v_mov_b32_e32 v74, v83
	v_mov_b32_e32 v75, v83
	v_mov_b32_e32 v76, v83
	v_mov_b32_e32 v77, v83
	v_mov_b32_e32 v78, v83
	v_mov_b32_e32 v79, v83
	v_and_b32_e32 v244, 63, v114
	v_mul_u32_u24_e32 v240, 0x3000, v244
	v_lshrrev_b32_e32 v242, 5, v244
	v_mul_u32_u24_e32 v242, 0x18000, v242
	v_sub_u32_e32 v240, v240, v242
	v_and_b32_e32 v242, 31, v244
	v_lshlrev_b32_e32 v242, 2, v242
	v_sub_u32_e32 v240, v240, v242
	v_add_co_u32_e32 v242, vcc, v240, v90
	s_nop 1
	v_addc_co_u32_e32 v243, vcc, 0, v91, vcc
	global_load_dword v240, v[242:243], off
	v_add_co_u32_e32 v242, vcc, 0xc0000, v242
	s_nop 1
	v_addc_co_u32_e32 v243, vcc, 0, v243, vcc
	global_load_dword v240, v[242:243], off
